# v009 plus: MLP-up clears each accumulator right behind its last use in the store-bound tile epilogue instead of in front of the next K loop
# speedup vs baseline: 1.0027x; 1.0027x over previous
.LBB0_551:
	v_lshrrev_b32_e32 v18, 1, v16
	s_add_u32 s42, s40, 0x18000000
	v_and_b32_e32 v18, 24, v18
	s_addc_u32 s43, s41, 0
	v_and_b32_e32 v17, 15, v16
	v_lshlrev_b32_e32 v19, 1, v18
	v_lshlrev_b32_e32 v16, 2, v16
	s_lshl_b32 s21, s21, 5
	v_lshl_or_b32 v141, s28, 6, v17
	v_lshl_or_b32 v17, v17, 6, v19
	s_lshl_b32 s28, s28, 13
	v_and_b32_e32 v16, 32, v16
	s_and_b32 s21, s21, 0x60
	s_add_i32 m0, s59, 0x18000
	v_lshl_add_u64 v[8:9], v[8:9], 0, s[10:11]
	v_bitop3_b32 v19, v17, s28, v16 bitop3:0xde
	s_lshl_b32 s28, s21, 7
	s_waitcnt vmcnt(2)
	s_barrier
	global_load_lds_dwordx4 v[8:9], off
	v_lshl_add_u64 v[6:7], v[6:7], 0, s[10:11]
	s_add_i32 m0, s59, 0x1a000
	s_add_i32 s63, s59, 0x8000
	s_add_i32 s64, s59, 0xa000
	v_bitop3_b32 v145, v17, s28, v16 bitop3:0xde
	global_load_lds_dwordx4 v[6:7], off
	v_lshl_add_u64 v[2:3], v[2:3], 0, s[10:11]
	s_mov_b32 m0, s63
	s_add_u32 s28, s12, 0x40080
	global_load_lds_dwordx4 v[2:3], off
	v_lshl_add_u64 v[2:3], v[4:5], 0, s[10:11]
	s_mov_b32 m0, s64
	s_addc_u32 s29, s13, 0
	global_load_lds_dwordx4 v[2:3], off
	s_add_i32 m0, s59, 0x1c000
	v_lshl_add_u64 v[2:3], s[28:29], 0, v[0:1]
	global_load_lds_dwordx4 v[2:3], off
	v_lshl_add_u64 v[2:3], s[28:29], 0, v[130:131]
	s_add_i32 m0, s59, 0x1e000
	s_cmpk_lt_u32 s20, 0x100
	global_load_lds_dwordx4 v[2:3], off
	v_lshlrev_b32_e32 v2, 14, v10
	v_and_b32_e32 v2, 0xffff8000, v2
	v_lshl_add_u32 v2, v11, 11, v2
	v_and_b32_e32 v3, 1, v10
	v_lshl_or_b32 v2, v3, 6, v2
	v_lshl_add_u32 v136, v12, 1, v2
	v_lshlrev_b32_e32 v2, 14, v14
	v_and_b32_e32 v2, 0xffff8000, v2
	s_waitcnt vmcnt(6)
	v_lshl_add_u32 v2, v13, 11, v2
	v_and_b32_e32 v3, 1, v14
	v_lshl_or_b32 v2, v3, 6, v2
	v_readlane_b32 s26, v255, 63
	s_cselect_b64 s[44:45], -1, 0
	s_waitcnt vmcnt(0)
	v_or_b32_e32 v147, s21, v18
	v_mov_b32_e32 v137, v1
	v_lshl_add_u32 v138, v15, 1, v2
	v_mov_b32_e32 v139, v1
	s_mov_b32 s65, 0
	v_add_u32_e32 v149, 0, v19
	v_readlane_b32 s20, v255, 56
	s_mov_b32 s21, s26
	s_barrier
	v_readlane_b32 s27, v254, 0
	v_lshl_add_u32 v238, s21, 8, v141
	v_mov_b32_e32 v239, 0
	v_lshl_add_u64 v[238:239], v[238:239], 2, s[4:5]
	global_load_dword v240, v[238:239], off
	global_load_dword v241, v[238:239], off offset:64
	global_load_dword v242, v[238:239], off offset:128
	global_load_dword v243, v[238:239], off offset:192
	global_load_dword v244, v[238:239], off offset:512
	global_load_dword v245, v[238:239], off offset:576
	global_load_dword v246, v[238:239], off offset:640
	global_load_dword v247, v[238:239], off offset:704
	v_mov_b32_e32 v6, 0
	v_mov_b32_e32 v7, 0
	v_mov_b32_e32 v8, 0
	v_mov_b32_e32 v9, 0
	v_mov_b32_e32 v10, 0
	v_mov_b32_e32 v11, 0
	v_mov_b32_e32 v12, 0
	v_mov_b32_e32 v13, 0
	v_mov_b32_e32 v14, 0
	v_mov_b32_e32 v15, 0
	v_mov_b32_e32 v16, 0
	v_mov_b32_e32 v17, 0
	v_mov_b32_e32 v20, 0
	v_mov_b32_e32 v21, 0
	v_mov_b32_e32 v22, 0
	v_mov_b32_e32 v23, 0
	v_mov_b32_e32 v24, 0
	v_mov_b32_e32 v25, 0
	v_mov_b32_e32 v26, 0
	v_mov_b32_e32 v27, 0
	v_mov_b32_e32 v28, 0
	v_mov_b32_e32 v29, 0
	v_mov_b32_e32 v30, 0
	v_mov_b32_e32 v31, 0
	v_mov_b32_e32 v32, 0
	v_mov_b32_e32 v33, 0
	v_mov_b32_e32 v34, 0
	v_mov_b32_e32 v35, 0
	v_mov_b32_e32 v36, 0
	v_mov_b32_e32 v37, 0
	v_mov_b32_e32 v38, 0
	v_mov_b32_e32 v39, 0
	v_mov_b32_e32 v40, 0
	v_mov_b32_e32 v41, 0
	v_mov_b32_e32 v42, 0
	v_mov_b32_e32 v43, 0
	v_mov_b32_e32 v44, 0
	v_mov_b32_e32 v45, 0
	v_mov_b32_e32 v46, 0
	v_mov_b32_e32 v47, 0
	v_mov_b32_e32 v48, 0
	v_mov_b32_e32 v49, 0
	v_mov_b32_e32 v50, 0
	v_mov_b32_e32 v51, 0
	v_mov_b32_e32 v52, 0
	v_mov_b32_e32 v53, 0
	v_mov_b32_e32 v54, 0
	v_mov_b32_e32 v55, 0
	v_mov_b32_e32 v56, 0
	v_mov_b32_e32 v57, 0
	v_mov_b32_e32 v58, 0
	v_mov_b32_e32 v59, 0
	v_mov_b32_e32 v60, 0
	v_mov_b32_e32 v61, 0
	v_mov_b32_e32 v62, 0
	v_mov_b32_e32 v63, 0
	v_mov_b32_e32 v64, 0
	v_mov_b32_e32 v65, 0
	v_mov_b32_e32 v66, 0
	v_mov_b32_e32 v67, 0
	v_mov_b32_e32 v68, 0
	v_mov_b32_e32 v69, 0
	v_mov_b32_e32 v70, 0
	v_mov_b32_e32 v71, 0
	v_mov_b32_e32 v72, 0
	v_mov_b32_e32 v73, 0
	v_mov_b32_e32 v74, 0
	v_mov_b32_e32 v75, 0
	v_mov_b32_e32 v76, 0
	v_mov_b32_e32 v77, 0
	v_mov_b32_e32 v78, 0
	v_mov_b32_e32 v79, 0
	v_mov_b32_e32 v80, 0
	v_mov_b32_e32 v81, 0
	v_mov_b32_e32 v82, 0
	v_mov_b32_e32 v83, 0
	v_mov_b32_e32 v84, 0
	v_mov_b32_e32 v85, 0
	v_mov_b32_e32 v86, 0
	v_mov_b32_e32 v87, 0
	v_mov_b32_e32 v88, 0
	v_mov_b32_e32 v89, 0
	v_mov_b32_e32 v90, 0
	v_mov_b32_e32 v91, 0
	v_mov_b32_e32 v92, 0
	v_mov_b32_e32 v93, 0
	v_mov_b32_e32 v94, 0
	v_mov_b32_e32 v95, 0
	v_mov_b32_e32 v96, 0
	v_mov_b32_e32 v97, 0
	v_mov_b32_e32 v98, 0
	v_mov_b32_e32 v99, 0
	v_mov_b32_e32 v100, 0
	v_mov_b32_e32 v101, 0
	v_mov_b32_e32 v102, 0
	v_mov_b32_e32 v103, 0
	v_mov_b32_e32 v104, 0
	v_mov_b32_e32 v105, 0
	v_mov_b32_e32 v106, 0
	v_mov_b32_e32 v107, 0
	v_mov_b32_e32 v108, 0
	v_mov_b32_e32 v109, 0
	v_mov_b32_e32 v110, 0
	v_mov_b32_e32 v111, 0
	v_mov_b32_e32 v112, 0
	v_mov_b32_e32 v113, 0
	v_mov_b32_e32 v114, 0
	v_mov_b32_e32 v115, 0
	v_mov_b32_e32 v116, 0
	v_mov_b32_e32 v117, 0
	v_mov_b32_e32 v118, 0
	v_mov_b32_e32 v119, 0
	v_mov_b32_e32 v120, 0
	v_mov_b32_e32 v121, 0
	v_mov_b32_e32 v122, 0
	v_mov_b32_e32 v123, 0
	v_mov_b32_e32 v124, 0
	v_mov_b32_e32 v125, 0
	v_mov_b32_e32 v126, 0
	v_mov_b32_e32 v127, 0
	v_mov_b32_e32 v128, 0
	v_mov_b32_e32 v129, 0
	s_branch .LBB0_554

.LBB0_560:
	s_ashr_i32 s49, s48, 31
	s_lshl_b64 s[28:29], s[48:49], 19
	s_add_u32 s50, s0, s28
	s_addc_u32 s51, s17, s29
	s_and_b64 s[28:29], s[40:41], exec
	s_cselect_b32 s28, s51, s15
	s_cselect_b32 s29, s50, s14
	s_ashr_i32 s47, s46, 31
	s_lshl_b64 s[36:37], s[46:47], 19
	s_add_u32 s52, s56, s36
	s_addc_u32 s53, s57, s37
	s_and_b64 s[36:37], s[40:41], exec
	s_cselect_b32 s33, s53, s13
	s_cselect_b32 s36, s52, s12
	s_add_u32 s37, s12, 0x100
	s_addc_u32 s47, s13, 0
	s_add_u32 s12, s14, 0x40080
	v_mov_b32_e32 v2, 0
	s_addc_u32 s13, s15, 0
	s_mov_b32 s49, -2
	v_mov_b32_e32 v3, v2
	v_mov_b32_e32 v4, v2
	v_mov_b32_e32 v5, v2
	v_mov_b32_e32 v18, v2
	v_mov_b32_e32 v19, v2

.LBB0_564:
	v_lshl_add_u32 v150, s21, 8, v141
	v_ashrrev_i32_e32 v151, 31, v150
	s_and_b64 s[12:13], s[40:41], exec
	s_cselect_b32 s12, s48, s21
	v_lshl_add_u32 v238, s12, 8, v141
	v_mov_b32_e32 v239, 0
	v_lshl_add_u64 v[238:239], v[238:239], 2, s[4:5]
	s_mov_b64 s[12:13], 0x100000
	s_waitcnt vmcnt(8)
	v_fmamk_f32 v140, v240, 0x3a800000, v225
	v_rsq_f32_e32 v160, v140
	v_fmamk_f32 v144, v241, 0x3a800000, v225
	v_rsq_f32_e32 v158, v144
	v_fmamk_f32 v153, v244, 0x3a800000, v225
	v_pk_mul_f32 v[122:123], v[122:123], v[160:161] op_sel_hi:[1,0]
	v_pk_mul_f32 v[126:127], v[126:127], v[160:161] op_sel_hi:[1,0]
	v_pk_mul_f32 v[124:125], v[124:125], v[160:161] op_sel_hi:[1,0]
	v_max_f32_e32 v122, 0, v122
	v_pk_mul_f32 v[128:129], v[128:129], v[160:161] op_sel_hi:[1,0]
	v_max_f32_e32 v123, 0, v123
	v_max_f32_e32 v124, 0, v124
	v_max_f32_e32 v126, 0, v126
	v_max_f32_e32 v125, 0, v125
	v_pk_mul_f32 v[114:115], v[114:115], v[160:161] op_sel_hi:[1,0]
	v_mul_f32_e32 v126, v126, v126
	v_mul_f32_e32 v125, v125, v125
	v_pk_mul_f32 v[118:119], v[118:119], v[160:161] op_sel_hi:[1,0]
	v_pk_mul_f32 v[116:117], v[116:117], v[160:161] op_sel_hi:[1,0]
	v_max_f32_e32 v114, 0, v114
	v_pk_mul_f32 v[120:121], v[120:121], v[160:161] op_sel_hi:[1,0]
	v_max_f32_e32 v115, 0, v115
	v_max_f32_e32 v116, 0, v116
	v_max_f32_e32 v118, 0, v118
	v_max_f32_e32 v117, 0, v117
	v_mul_f32_e32 v118, v118, v118
	v_mul_f32_e32 v117, v117, v117
	v_pk_mul_f32 v[106:107], v[106:107], v[158:159] op_sel_hi:[1,0]
	v_pk_mul_f32 v[110:111], v[110:111], v[158:159] op_sel_hi:[1,0]
	v_pk_mul_f32 v[108:109], v[108:109], v[158:159] op_sel_hi:[1,0]
	v_max_f32_e32 v106, 0, v106
	v_pk_mul_f32 v[112:113], v[112:113], v[158:159] op_sel_hi:[1,0]
	v_max_f32_e32 v107, 0, v107
	v_max_f32_e32 v108, 0, v108
	v_fmamk_f32 v146, v242, 0x3a800000, v225
	v_max_f32_e32 v110, 0, v110
	v_max_f32_e32 v109, 0, v109
	v_pk_mul_f32 v[98:99], v[98:99], v[158:159] op_sel_hi:[1,0]
	v_rsq_f32_e32 v154, v146
	v_mul_f32_e32 v110, v110, v110
	v_mul_f32_e32 v109, v109, v109
	v_pk_mul_f32 v[102:103], v[102:103], v[158:159] op_sel_hi:[1,0]
	v_pk_mul_f32 v[100:101], v[100:101], v[158:159] op_sel_hi:[1,0]
	v_max_f32_e32 v98, 0, v98
	v_pk_mul_f32 v[104:105], v[104:105], v[158:159] op_sel_hi:[1,0]
	v_max_f32_e32 v99, 0, v99
	v_max_f32_e32 v100, 0, v100
	v_max_f32_e32 v102, 0, v102
	v_max_f32_e32 v101, 0, v101
	v_mul_f32_e32 v102, v102, v102
	v_mul_f32_e32 v101, v101, v101
	v_fmamk_f32 v148, v243, 0x3a800000, v225
	v_fmamk_f32 v155, v245, 0x3a800000, v225
	v_pk_mul_f32 v[90:91], v[90:91], v[154:155] op_sel_hi:[1,0]
	v_pk_mul_f32 v[94:95], v[94:95], v[154:155] op_sel_hi:[1,0]
	v_pk_mul_f32 v[92:93], v[92:93], v[154:155] op_sel_hi:[1,0]
	v_max_f32_e32 v90, 0, v90
	v_pk_mul_f32 v[96:97], v[96:97], v[154:155] op_sel_hi:[1,0]
	v_max_f32_e32 v91, 0, v91
	v_max_f32_e32 v92, 0, v92
	v_max_f32_e32 v94, 0, v94
	v_max_f32_e32 v93, 0, v93
	v_pk_mul_f32 v[82:83], v[82:83], v[154:155] op_sel_hi:[1,0]
	v_mul_f32_e32 v94, v94, v94
	v_mul_f32_e32 v93, v93, v93
	v_pk_mul_f32 v[86:87], v[86:87], v[154:155] op_sel_hi:[1,0]
	v_pk_mul_f32 v[84:85], v[84:85], v[154:155] op_sel_hi:[1,0]
	v_max_f32_e32 v82, 0, v82
	v_pk_mul_f32 v[88:89], v[88:89], v[154:155] op_sel_hi:[1,0]
	v_max_f32_e32 v83, 0, v83
	v_max_f32_e32 v84, 0, v84
	v_max_f32_e32 v86, 0, v86
	v_max_f32_e32 v85, 0, v85
	v_mul_f32_e32 v86, v86, v86
	v_mul_f32_e32 v85, v85, v85
	v_rsq_f32_e32 v146, v155
	v_fmamk_f32 v156, v246, 0x3a800000, v225
	v_rsq_f32_e32 v144, v156
	v_fmamk_f32 v142, v247, 0x3a800000, v225
	v_rsq_f32_e32 v140, v142
	global_load_dword v240, v[238:239], off
	global_load_dword v241, v[238:239], off offset:64
	global_load_dword v242, v[238:239], off offset:128
	global_load_dword v243, v[238:239], off offset:192
	global_load_dword v244, v[238:239], off offset:512
	global_load_dword v245, v[238:239], off offset:576
	global_load_dword v246, v[238:239], off offset:640
	global_load_dword v247, v[238:239], off offset:704
	v_lshl_or_b32 v142, s20, 8, v147
	v_ashrrev_i32_e32 v143, 31, v142
	v_lshlrev_b64 v[156:157], 13, v[150:151]
	v_mul_f32_e32 v151, v122, v122
	v_max_f32_e32 v122, 0, v127
	v_lshl_add_u64 v[162:163], s[42:43], 0, v[156:157]
	v_lshlrev_b64 v[156:157], 1, v[142:143]
	v_mul_f32_e32 v122, v122, v122
	v_mul_f32_e32 v127, v123, v123
	v_max_f32_e32 v123, 0, v128
	v_mul_f32_e32 v128, v124, v124
	v_max_f32_e32 v124, 0, v129
	v_mov_b32_e32 v129, 0
	v_lshl_add_u64 v[142:143], v[162:163], 0, v[156:157]
	v_mul_f32_e32 v123, v123, v123
	v_mul_f32_e32 v124, v124, v124
	v_cvt_pk_bf16_f32 v122, v126, v122
	v_mov_b32_e32 v126, 0
	v_cvt_pk_bf16_f32 v123, v123, v124
	v_cvt_pk_bf16_f32 v124, v151, v127
	v_mov_b32_e32 v127, 0
	v_cvt_pk_bf16_f32 v125, v128, v125
	v_mov_b32_e32 v128, 0
	flat_store_dwordx4 v[142:143], v[122:125] nt
	v_rsq_f32_e32 v152, v148
	v_rsq_f32_e32 v148, v153
	v_mov_b32_e32 v123, 0
	v_mov_b32_e32 v124, 0
	v_mov_b32_e32 v125, 0
	v_mul_f32_e32 v122, v114, v114
	v_max_f32_e32 v114, 0, v119
	v_mul_f32_e32 v114, v114, v114
	v_mul_f32_e32 v119, v115, v115
	v_max_f32_e32 v115, 0, v120
	v_mul_f32_e32 v120, v116, v116
	v_max_f32_e32 v116, 0, v121
	v_mov_b32_e32 v121, 0
	v_mul_f32_e32 v115, v115, v115
	v_mul_f32_e32 v116, v116, v116
	v_cvt_pk_bf16_f32 v114, v118, v114
	v_mov_b32_e32 v118, 0
	v_cvt_pk_bf16_f32 v115, v115, v116
	v_cvt_pk_bf16_f32 v116, v122, v119
	v_mov_b32_e32 v119, 0
	v_mov_b32_e32 v122, 0
	v_cvt_pk_bf16_f32 v117, v120, v117
	v_mov_b32_e32 v120, 0
	flat_store_dwordx4 v[142:143], v[114:117] offset:256 nt
	v_pk_mul_f32 v[74:75], v[74:75], v[152:153] op_sel_hi:[1,0]
	v_pk_mul_f32 v[78:79], v[78:79], v[152:153] op_sel_hi:[1,0]
	v_mov_b32_e32 v117, 0
	v_or_b32_e32 v114, 16, v150
	v_ashrrev_i32_e32 v115, 31, v114
	v_lshlrev_b64 v[114:115], 13, v[114:115]
	v_mul_f32_e32 v116, v106, v106
	v_max_f32_e32 v106, 0, v111
	v_lshl_add_u64 v[114:115], s[42:43], 0, v[114:115]
	v_mul_f32_e32 v106, v106, v106
	v_mul_f32_e32 v111, v107, v107
	v_max_f32_e32 v107, 0, v112
	v_mul_f32_e32 v112, v108, v108
	v_max_f32_e32 v108, 0, v113
	v_mov_b32_e32 v113, 0
	v_lshl_add_u64 v[114:115], v[114:115], 0, v[156:157]
	v_mul_f32_e32 v107, v107, v107
	v_mul_f32_e32 v108, v108, v108
	v_cvt_pk_bf16_f32 v106, v110, v106
	v_mov_b32_e32 v110, 0
	v_cvt_pk_bf16_f32 v107, v107, v108
	v_cvt_pk_bf16_f32 v108, v116, v111
	v_mov_b32_e32 v111, 0
	v_mov_b32_e32 v116, 0
	v_cvt_pk_bf16_f32 v109, v112, v109
	v_mov_b32_e32 v112, 0
	flat_store_dwordx4 v[114:115], v[106:109] nt
	v_pk_mul_f32 v[76:77], v[76:77], v[152:153] op_sel_hi:[1,0]
	v_max_f32_e32 v74, 0, v74
	v_mov_b32_e32 v107, 0
	v_mov_b32_e32 v108, 0
	v_mov_b32_e32 v109, 0
	v_mul_f32_e32 v106, v98, v98
	v_max_f32_e32 v98, 0, v103
	v_mul_f32_e32 v98, v98, v98
	v_mul_f32_e32 v103, v99, v99
	v_max_f32_e32 v99, 0, v104
	v_mul_f32_e32 v104, v100, v100
	v_max_f32_e32 v100, 0, v105
	v_mov_b32_e32 v105, 0
	v_mul_f32_e32 v99, v99, v99
	v_mul_f32_e32 v100, v100, v100
	v_cvt_pk_bf16_f32 v98, v102, v98
	v_mov_b32_e32 v102, 0
	v_cvt_pk_bf16_f32 v99, v99, v100
	v_cvt_pk_bf16_f32 v100, v106, v103
	v_mov_b32_e32 v103, 0
	v_mov_b32_e32 v106, 0
	v_cvt_pk_bf16_f32 v101, v104, v101
	v_mov_b32_e32 v104, 0
	flat_store_dwordx4 v[114:115], v[98:101] offset:256 nt
	v_pk_mul_f32 v[80:81], v[80:81], v[152:153] op_sel_hi:[1,0]
	v_max_f32_e32 v75, 0, v75
	v_mov_b32_e32 v101, 0
	v_mov_b32_e32 v114, 0
	v_mov_b32_e32 v115, 0
	v_or_b32_e32 v98, 32, v150
	v_ashrrev_i32_e32 v99, 31, v98
	v_lshlrev_b64 v[98:99], 13, v[98:99]
	v_mul_f32_e32 v100, v90, v90
	v_max_f32_e32 v90, 0, v95
	v_lshl_add_u64 v[98:99], s[42:43], 0, v[98:99]
	v_mul_f32_e32 v90, v90, v90
	v_mul_f32_e32 v95, v91, v91
	v_max_f32_e32 v91, 0, v96
	v_mul_f32_e32 v96, v92, v92
	v_max_f32_e32 v92, 0, v97
	v_mov_b32_e32 v97, 0
	v_lshl_add_u64 v[98:99], v[98:99], 0, v[156:157]
	v_mul_f32_e32 v91, v91, v91
	v_mul_f32_e32 v92, v92, v92
	v_cvt_pk_bf16_f32 v90, v94, v90
	v_mov_b32_e32 v94, 0
	v_cvt_pk_bf16_f32 v91, v91, v92
	v_cvt_pk_bf16_f32 v92, v100, v95
	v_mov_b32_e32 v95, 0
	v_mov_b32_e32 v100, 0
	v_cvt_pk_bf16_f32 v93, v96, v93
	v_mov_b32_e32 v96, 0
	flat_store_dwordx4 v[98:99], v[90:93] nt
	v_max_f32_e32 v76, 0, v76
	v_max_f32_e32 v78, 0, v78
	v_mov_b32_e32 v91, 0
	v_mov_b32_e32 v92, 0
	v_mov_b32_e32 v93, 0
	v_mul_f32_e32 v90, v82, v82
	v_max_f32_e32 v82, 0, v87
	v_mul_f32_e32 v82, v82, v82
	v_mul_f32_e32 v87, v83, v83
	v_max_f32_e32 v83, 0, v88
	v_mul_f32_e32 v88, v84, v84
	v_max_f32_e32 v84, 0, v89
	v_mov_b32_e32 v89, 0
	v_mul_f32_e32 v83, v83, v83
	v_mul_f32_e32 v84, v84, v84
	v_cvt_pk_bf16_f32 v82, v86, v82
	v_mov_b32_e32 v86, 0
	v_cvt_pk_bf16_f32 v83, v83, v84
	v_cvt_pk_bf16_f32 v84, v90, v87
	v_mov_b32_e32 v87, 0
	v_mov_b32_e32 v90, 0
	v_cvt_pk_bf16_f32 v85, v88, v85
	v_mov_b32_e32 v88, 0
	flat_store_dwordx4 v[98:99], v[82:85] offset:256 nt
	v_max_f32_e32 v77, 0, v77
	v_pk_mul_f32 v[68:69], v[68:69], v[152:153] op_sel_hi:[1,0]
	v_mov_b32_e32 v85, 0
	v_mov_b32_e32 v98, 0
	v_mov_b32_e32 v99, 0
	v_or_b32_e32 v82, 48, v150
	v_ashrrev_i32_e32 v83, 31, v82
	v_lshlrev_b64 v[82:83], 13, v[82:83]
	v_mul_f32_e32 v84, v74, v74
	v_max_f32_e32 v74, 0, v79
	v_lshl_add_u64 v[82:83], s[42:43], 0, v[82:83]
	v_mul_f32_e32 v74, v74, v74
	v_mul_f32_e32 v79, v75, v75
	v_max_f32_e32 v75, 0, v80
	v_mul_f32_e32 v80, v76, v76
	v_max_f32_e32 v76, 0, v81
	v_mov_b32_e32 v81, 0
	v_pk_mul_f32 v[66:67], v[66:67], v[152:153] op_sel_hi:[1,0]
	v_lshl_add_u64 v[82:83], v[82:83], 0, v[156:157]
	v_mul_f32_e32 v78, v78, v78
	v_mul_f32_e32 v75, v75, v75
	v_mul_f32_e32 v76, v76, v76
	v_mul_f32_e32 v77, v77, v77
	v_cvt_pk_bf16_f32 v74, v78, v74
	v_mov_b32_e32 v78, 0
	v_pk_mul_f32 v[72:73], v[72:73], v[152:153] op_sel_hi:[1,0]
	v_pk_mul_f32 v[70:71], v[70:71], v[152:153] op_sel_hi:[1,0]
	v_max_f32_e32 v66, 0, v66
	v_max_f32_e32 v67, 0, v67
	v_max_f32_e32 v68, 0, v68
	v_cvt_pk_bf16_f32 v75, v75, v76
	v_cvt_pk_bf16_f32 v76, v84, v79
	v_mov_b32_e32 v79, 0
	v_mov_b32_e32 v84, 0
	v_cvt_pk_bf16_f32 v77, v80, v77
	v_mov_b32_e32 v80, 0
	flat_store_dwordx4 v[82:83], v[74:77] nt
	v_max_f32_e32 v70, 0, v70
	v_max_f32_e32 v69, 0, v69
	v_mov_b32_e32 v75, 0
	v_mov_b32_e32 v76, 0
	v_mov_b32_e32 v77, 0
	v_mul_f32_e32 v74, v66, v66
	v_max_f32_e32 v66, 0, v71
	v_mul_f32_e32 v71, v67, v67
	v_max_f32_e32 v67, 0, v72
	v_mul_f32_e32 v72, v68, v68
	v_max_f32_e32 v68, 0, v73
	v_mov_b32_e32 v73, 0
	v_mul_f32_e32 v66, v66, v66
	v_mul_f32_e32 v67, v67, v67
	v_mul_f32_e32 v68, v68, v68
	v_pk_mul_f32 v[58:59], v[58:59], v[148:149] op_sel_hi:[1,0]
	v_mul_f32_e32 v70, v70, v70
	v_mul_f32_e32 v69, v69, v69
	v_cvt_pk_bf16_f32 v66, v70, v66
	v_mov_b32_e32 v70, 0
	v_cvt_pk_bf16_f32 v67, v67, v68
	v_cvt_pk_bf16_f32 v68, v74, v71
	v_mov_b32_e32 v71, 0
	v_mov_b32_e32 v74, 0
	v_pk_mul_f32 v[62:63], v[62:63], v[148:149] op_sel_hi:[1,0]
	v_pk_mul_f32 v[60:61], v[60:61], v[148:149] op_sel_hi:[1,0]
	v_max_f32_e32 v58, 0, v58
	v_cvt_pk_bf16_f32 v69, v72, v69
	v_mov_b32_e32 v72, 0
	flat_store_dwordx4 v[82:83], v[66:69] offset:256 nt
	v_pk_mul_f32 v[64:65], v[64:65], v[148:149] op_sel_hi:[1,0]
	v_max_f32_e32 v62, 0, v62
	v_mov_b32_e32 v69, 0
	v_mov_b32_e32 v82, 0
	v_mov_b32_e32 v83, 0
	v_mul_f32_e32 v68, v58, v58
	v_max_f32_e32 v58, 0, v63
	v_max_f32_e32 v59, 0, v59
	v_max_f32_e32 v60, 0, v60
	v_lshl_add_u64 v[66:67], v[142:143], 0, s[12:13]
	v_mul_f32_e32 v62, v62, v62
	v_mul_f32_e32 v58, v58, v58
	v_mul_f32_e32 v63, v59, v59
	v_max_f32_e32 v59, 0, v64
	v_mul_f32_e32 v64, v60, v60
	v_max_f32_e32 v60, 0, v65
	v_mov_b32_e32 v65, 0
	s_mov_b32 s12, 0x100000
	v_mul_f32_e32 v59, v59, v59
	v_max_f32_e32 v61, 0, v61
	v_mul_f32_e32 v60, v60, v60
	v_cvt_pk_bf16_f32 v58, v62, v58
	v_add_co_u32_e32 v62, vcc, s12, v142
	v_pk_mul_f32 v[52:53], v[52:53], v[148:149] op_sel_hi:[1,0]
	v_pk_mul_f32 v[50:51], v[50:51], v[148:149] op_sel_hi:[1,0]
	v_mul_f32_e32 v61, v61, v61
	v_cvt_pk_bf16_f32 v59, v59, v60
	v_cvt_pk_bf16_f32 v60, v68, v63
	v_mov_b32_e32 v68, 0
	v_addc_co_u32_e32 v63, vcc, 0, v143, vcc
	v_pk_mul_f32 v[56:57], v[56:57], v[148:149] op_sel_hi:[1,0]
	v_pk_mul_f32 v[54:55], v[54:55], v[148:149] op_sel_hi:[1,0]
	v_max_f32_e32 v50, 0, v50
	v_max_f32_e32 v51, 0, v51
	v_max_f32_e32 v52, 0, v52
	v_cvt_pk_bf16_f32 v61, v64, v61
	v_mov_b32_e32 v64, 0
	flat_store_dwordx4 v[62:63], v[58:61] nt
	v_max_f32_e32 v54, 0, v54
	v_max_f32_e32 v53, 0, v53
	v_mov_b32_e32 v59, 0
	v_mov_b32_e32 v60, 0
	v_mov_b32_e32 v61, 0
	v_mov_b32_e32 v62, 0
	v_mov_b32_e32 v63, 0
	v_mul_f32_e32 v58, v50, v50
	v_max_f32_e32 v50, 0, v55
	v_mul_f32_e32 v55, v51, v51
	v_max_f32_e32 v51, 0, v56
	v_mul_f32_e32 v56, v52, v52
	v_max_f32_e32 v52, 0, v57
	v_mov_b32_e32 v57, 0
	v_mul_f32_e32 v50, v50, v50
	v_mul_f32_e32 v51, v51, v51
	v_mul_f32_e32 v52, v52, v52
	v_pk_mul_f32 v[42:43], v[42:43], v[146:147] op_sel_hi:[1,0]
	v_mul_f32_e32 v54, v54, v54
	v_mul_f32_e32 v53, v53, v53
	v_cvt_pk_bf16_f32 v50, v54, v50
	v_mov_b32_e32 v54, 0
	v_cvt_pk_bf16_f32 v51, v51, v52
	v_cvt_pk_bf16_f32 v52, v58, v55
	v_mov_b32_e32 v55, 0
	v_mov_b32_e32 v58, 0
	v_pk_mul_f32 v[46:47], v[46:47], v[146:147] op_sel_hi:[1,0]
	v_pk_mul_f32 v[44:45], v[44:45], v[146:147] op_sel_hi:[1,0]
	v_max_f32_e32 v42, 0, v42
	v_cvt_pk_bf16_f32 v53, v56, v53
	v_mov_b32_e32 v56, 0
	flat_store_dwordx4 v[66:67], v[50:53] offset:256 nt
	s_mov_b64 s[12:13], 0x120000
	v_pk_mul_f32 v[48:49], v[48:49], v[146:147] op_sel_hi:[1,0]
	v_mov_b32_e32 v53, 0
	v_mov_b32_e32 v66, 0
	v_mov_b32_e32 v67, 0
	v_max_f32_e32 v46, 0, v46
	v_mul_f32_e32 v52, v42, v42
	v_max_f32_e32 v42, 0, v47
	v_max_f32_e32 v43, 0, v43
	v_max_f32_e32 v44, 0, v44
	v_lshl_add_u64 v[50:51], v[142:143], 0, s[12:13]
	v_mul_f32_e32 v46, v46, v46
	v_mul_f32_e32 v42, v42, v42
	v_mul_f32_e32 v47, v43, v43
	v_max_f32_e32 v43, 0, v48
	v_mul_f32_e32 v48, v44, v44
	v_max_f32_e32 v44, 0, v49
	v_mov_b32_e32 v49, 0
	s_mov_b32 s12, 0x120000
	v_mul_f32_e32 v43, v43, v43
	v_max_f32_e32 v45, 0, v45
	v_mul_f32_e32 v44, v44, v44
	v_cvt_pk_bf16_f32 v42, v46, v42
	v_add_co_u32_e32 v46, vcc, s12, v142
	v_pk_mul_f32 v[36:37], v[36:37], v[146:147] op_sel_hi:[1,0]
	v_pk_mul_f32 v[34:35], v[34:35], v[146:147] op_sel_hi:[1,0]
	v_mul_f32_e32 v45, v45, v45
	v_cvt_pk_bf16_f32 v43, v43, v44
	v_cvt_pk_bf16_f32 v44, v52, v47
	v_mov_b32_e32 v52, 0
	v_addc_co_u32_e32 v47, vcc, 0, v143, vcc
	v_pk_mul_f32 v[40:41], v[40:41], v[146:147] op_sel_hi:[1,0]
	v_pk_mul_f32 v[38:39], v[38:39], v[146:147] op_sel_hi:[1,0]
	v_max_f32_e32 v34, 0, v34
	v_max_f32_e32 v35, 0, v35
	v_max_f32_e32 v36, 0, v36
	v_cvt_pk_bf16_f32 v45, v48, v45
	v_mov_b32_e32 v48, 0
	flat_store_dwordx4 v[46:47], v[42:45] nt
	v_max_f32_e32 v38, 0, v38
	v_max_f32_e32 v37, 0, v37
	v_mov_b32_e32 v43, 0
	v_mov_b32_e32 v44, 0
	v_mov_b32_e32 v45, 0
	v_mov_b32_e32 v46, 0
	v_mov_b32_e32 v47, 0
	v_mul_f32_e32 v42, v34, v34
	v_max_f32_e32 v34, 0, v39
	v_mul_f32_e32 v39, v35, v35
	v_max_f32_e32 v35, 0, v40
	v_mul_f32_e32 v40, v36, v36
	v_max_f32_e32 v36, 0, v41
	v_mov_b32_e32 v41, 0
	v_mul_f32_e32 v34, v34, v34
	v_mul_f32_e32 v35, v35, v35
	v_mul_f32_e32 v36, v36, v36
	v_pk_mul_f32 v[26:27], v[26:27], v[144:145] op_sel_hi:[1,0]
	v_mul_f32_e32 v38, v38, v38
	v_mul_f32_e32 v37, v37, v37
	v_cvt_pk_bf16_f32 v34, v38, v34
	v_mov_b32_e32 v38, 0
	v_cvt_pk_bf16_f32 v35, v35, v36
	v_cvt_pk_bf16_f32 v36, v42, v39
	v_mov_b32_e32 v39, 0
	v_mov_b32_e32 v42, 0
	v_pk_mul_f32 v[30:31], v[30:31], v[144:145] op_sel_hi:[1,0]
	v_pk_mul_f32 v[28:29], v[28:29], v[144:145] op_sel_hi:[1,0]
	v_max_f32_e32 v26, 0, v26
	v_cvt_pk_bf16_f32 v37, v40, v37
	v_mov_b32_e32 v40, 0
	flat_store_dwordx4 v[50:51], v[34:37] offset:256 nt
	s_mov_b64 s[12:13], 0x140000
	v_pk_mul_f32 v[32:33], v[32:33], v[144:145] op_sel_hi:[1,0]
	v_mov_b32_e32 v37, 0
	v_mov_b32_e32 v50, 0
	v_mov_b32_e32 v51, 0
	v_max_f32_e32 v30, 0, v30
	v_mul_f32_e32 v36, v26, v26
	v_max_f32_e32 v26, 0, v31
	v_max_f32_e32 v27, 0, v27
	v_max_f32_e32 v28, 0, v28
	v_lshl_add_u64 v[34:35], v[142:143], 0, s[12:13]
	v_mul_f32_e32 v30, v30, v30
	v_mul_f32_e32 v26, v26, v26
	v_mul_f32_e32 v31, v27, v27
	v_max_f32_e32 v27, 0, v32
	v_mul_f32_e32 v32, v28, v28
	v_max_f32_e32 v28, 0, v33
	v_mov_b32_e32 v33, 0
	s_mov_b32 s12, 0x140000
	v_mul_f32_e32 v27, v27, v27
	v_max_f32_e32 v29, 0, v29
	v_mul_f32_e32 v28, v28, v28
	v_cvt_pk_bf16_f32 v26, v30, v26
	v_add_co_u32_e32 v30, vcc, s12, v142
	v_pk_mul_f32 v[20:21], v[20:21], v[144:145] op_sel_hi:[1,0]
	v_pk_mul_f32 v[18:19], v[18:19], v[144:145] op_sel_hi:[1,0]
	v_mul_f32_e32 v29, v29, v29
	v_cvt_pk_bf16_f32 v27, v27, v28
	v_cvt_pk_bf16_f32 v28, v36, v31
	v_mov_b32_e32 v36, 0
	v_addc_co_u32_e32 v31, vcc, 0, v143, vcc
	v_pk_mul_f32 v[24:25], v[24:25], v[144:145] op_sel_hi:[1,0]
	v_pk_mul_f32 v[22:23], v[22:23], v[144:145] op_sel_hi:[1,0]
	v_max_f32_e32 v18, 0, v18
	v_max_f32_e32 v19, 0, v19
	v_max_f32_e32 v20, 0, v20
	v_cvt_pk_bf16_f32 v29, v32, v29
	v_mov_b32_e32 v32, 0
	flat_store_dwordx4 v[30:31], v[26:29] nt
	v_max_f32_e32 v22, 0, v22
	v_max_f32_e32 v21, 0, v21
	v_mov_b32_e32 v27, 0
	v_mov_b32_e32 v28, 0
	v_mov_b32_e32 v29, 0
	v_mov_b32_e32 v30, 0
	v_mov_b32_e32 v31, 0
	v_mul_f32_e32 v26, v18, v18
	v_max_f32_e32 v18, 0, v23
	v_mul_f32_e32 v23, v19, v19
	v_max_f32_e32 v19, 0, v24
	v_mul_f32_e32 v24, v20, v20
	v_max_f32_e32 v20, 0, v25
	v_mov_b32_e32 v25, 0
	v_mul_f32_e32 v18, v18, v18
	v_mul_f32_e32 v19, v19, v19
	v_mul_f32_e32 v20, v20, v20
	v_pk_mul_f32 v[10:11], v[10:11], v[140:141] op_sel_hi:[1,0]
	v_mul_f32_e32 v22, v22, v22
	v_mul_f32_e32 v21, v21, v21
	v_cvt_pk_bf16_f32 v18, v22, v18
	v_mov_b32_e32 v22, 0
	v_cvt_pk_bf16_f32 v19, v19, v20
	v_cvt_pk_bf16_f32 v20, v26, v23
	v_mov_b32_e32 v23, 0
	v_mov_b32_e32 v26, 0
	v_pk_mul_f32 v[14:15], v[14:15], v[140:141] op_sel_hi:[1,0]
	v_pk_mul_f32 v[12:13], v[12:13], v[140:141] op_sel_hi:[1,0]
	v_max_f32_e32 v10, 0, v10
	v_cvt_pk_bf16_f32 v21, v24, v21
	v_mov_b32_e32 v24, 0
	flat_store_dwordx4 v[34:35], v[18:21] offset:256 nt
	s_mov_b64 s[12:13], 0x160000
	v_pk_mul_f32 v[16:17], v[16:17], v[140:141] op_sel_hi:[1,0]
	v_mov_b32_e32 v21, 0
	v_mov_b32_e32 v34, 0
	v_mov_b32_e32 v35, 0
	v_max_f32_e32 v14, 0, v14
	v_mul_f32_e32 v20, v10, v10
	v_max_f32_e32 v10, 0, v15
	v_max_f32_e32 v11, 0, v11
	v_max_f32_e32 v12, 0, v12
	v_lshl_add_u64 v[18:19], v[142:143], 0, s[12:13]
	v_mul_f32_e32 v14, v14, v14
	v_mul_f32_e32 v10, v10, v10
	v_mul_f32_e32 v15, v11, v11
	v_max_f32_e32 v11, 0, v16
	v_mul_f32_e32 v16, v12, v12
	v_max_f32_e32 v12, 0, v17
	v_mov_b32_e32 v17, 0
	s_mov_b32 s12, 0x160000
	v_mul_f32_e32 v11, v11, v11
	v_max_f32_e32 v13, 0, v13
	v_mul_f32_e32 v12, v12, v12
	v_cvt_pk_bf16_f32 v10, v14, v10
	v_add_co_u32_e32 v14, vcc, s12, v142
	v_pk_mul_f32 v[4:5], v[4:5], v[140:141] op_sel_hi:[1,0]
	v_pk_mul_f32 v[2:3], v[2:3], v[140:141] op_sel_hi:[1,0]
	v_mul_f32_e32 v13, v13, v13
	v_cvt_pk_bf16_f32 v11, v11, v12
	v_cvt_pk_bf16_f32 v12, v20, v15
	v_mov_b32_e32 v20, 0
	v_addc_co_u32_e32 v15, vcc, 0, v143, vcc
	v_pk_mul_f32 v[8:9], v[8:9], v[140:141] op_sel_hi:[1,0]
	v_pk_mul_f32 v[6:7], v[6:7], v[140:141] op_sel_hi:[1,0]
	v_max_f32_e32 v2, 0, v2
	v_max_f32_e32 v3, 0, v3
	v_max_f32_e32 v4, 0, v4
	v_cvt_pk_bf16_f32 v13, v16, v13
	v_mov_b32_e32 v16, 0
	flat_store_dwordx4 v[14:15], v[10:13] nt
	v_max_f32_e32 v5, 0, v5
	v_max_f32_e32 v6, 0, v6
	v_mov_b32_e32 v11, 0
	v_mov_b32_e32 v12, 0
	v_mov_b32_e32 v13, 0
	v_mov_b32_e32 v14, 0
	v_mov_b32_e32 v15, 0
	v_mul_f32_e32 v10, v2, v2
	v_max_f32_e32 v2, 0, v7
	v_mul_f32_e32 v7, v3, v3
	v_max_f32_e32 v3, 0, v8
	v_mul_f32_e32 v8, v4, v4
	v_max_f32_e32 v4, 0, v9
	v_mov_b32_e32 v9, 0
	v_mul_f32_e32 v2, v2, v2
	v_mul_f32_e32 v3, v3, v3
	v_mul_f32_e32 v4, v4, v4
	v_mul_f32_e32 v5, v5, v5
	s_mov_b64 s[12:13], -1
	s_andn2_b64 vcc, exec, s[40:41]
	v_mul_f32_e32 v6, v6, v6
	v_cvt_pk_bf16_f32 v2, v6, v2
	v_mov_b32_e32 v6, 0
	v_cvt_pk_bf16_f32 v3, v3, v4
	v_cvt_pk_bf16_f32 v4, v10, v7
	v_mov_b32_e32 v7, 0
	v_mov_b32_e32 v10, 0
	v_cvt_pk_bf16_f32 v5, v8, v5
	v_mov_b32_e32 v8, 0
	flat_store_dwordx4 v[18:19], v[2:5] offset:256 nt
	s_cbranch_vccnz .LBB0_553
	s_andn2_b64 vcc, exec, s[18:19]
	s_cbranch_vccnz .LBB0_552
	s_barrier
	s_branch .LBB0_552
